# GEMM mainloop: pre-barrier lgkmcnt(0) only for the lagging wave group (leading group's reads are covered by its own post-barrier wait)
# baseline (speedup 1.0000x reference)
; #define WAIT_V(n) asm volatile("s_waitcnt vmcnt(" #n ")" ::: "memory")
; #define RAWBAR() do { asm volatile("s_waitcnt lgkmcnt(0)" ::: "memory"); __builtin_amdgcn_s_barrier(); asm volatile("" ::: "memory"); } while (0)
; template <class PF, class EF>
; DI void gemm_stream(int lda, int ldw, int K, unsigned char* smem, PF ptrs, EF epi) {
;     ...
;       if (hh + 3 < nh) { H_DMA(sbase + ((rs + 3) & 3) * SLOT); ap += 64; bp += 64; }
;       if (wm == 1) {
;         if (rem >= 2) WAIT_V(8); else if (rem == 1) WAIT_V(4); else WAIT_V(0);
;       }
;       __builtin_amdgcn_sched_barrier(0);
;       RAWBAR();
;       __builtin_amdgcn_sched_barrier(0);
.LBB0_223:
	s_and_saveexec_b64 s[8:9], s[2:3]
	s_cbranch_execz .LBB0_232
	s_waitcnt lgkmcnt(0)
	s_mov_b64 s[10:11], -1
	s_and_b64 vcc, exec, s[6:7]
	s_cbranch_vccz .LBB0_230
	s_cmp_lg_u32 s14, 29
	s_cbranch_scc0 .LBB0_227
	s_waitcnt vmcnt(0)
	s_mov_b64 s[10:11], 0

; #define WAIT_V(n) asm volatile("s_waitcnt vmcnt(" #n ")" ::: "memory")
; #define RAWBAR() do { asm volatile("s_waitcnt lgkmcnt(0)" ::: "memory"); __builtin_amdgcn_s_barrier(); asm volatile("" ::: "memory"); } while (0)
; #define BAR0() do { asm volatile("" ::: "memory"); __builtin_amdgcn_s_barrier(); asm volatile("" ::: "memory"); } while (0)
; #define H_MMA() do { _Pragma("unroll") for (int ks = 0; ks < 2; ++ks) { _Pragma("unroll") for (int mi = 0; mi < 4; ++mi) {  \
;       acc[mi][0] = MFMA(fa[ks][mi], fb[ks][0], acc[mi][0]);                                                       \
;       acc[mi][1] = MFMA(fa[ks][mi], fb[ks][1], acc[mi][1]); } } } while (0)
; template <class PF, class EF>
; DI void gemm_stream(int lda, int ldw, int K, unsigned char* smem, PF ptrs, EF epi) {
;     ...
;       RAWBAR();
;       __builtin_amdgcn_sched_barrier(0);
;       H_MMA();
;       __builtin_amdgcn_sched_barrier(0);
;       if (wm == 0) {
;         if (rem >= 2) WAIT_V(8); else if (rem == 1) WAIT_V(4); else WAIT_V(0);
;       }
;       BAR0();
.LBB0_232:
	s_or_b64 exec, exec, s[8:9]
	s_barrier
	s_waitcnt lgkmcnt(0)
	v_mfma_f32_32x32x16_bf16 v[64:79], v[164:167], v[168:171], v[64:79]
	v_mfma_f32_32x32x16_bf16 v[96:111], v[164:167], v[172:175], v[96:111]
	v_mfma_f32_32x32x16_bf16 v[80:95], v[160:163], v[168:171], v[80:95]
	v_mfma_f32_32x32x16_bf16 v[112:127], v[160:163], v[172:175], v[112:127]
	v_mfma_f32_32x32x16_bf16 v[0:15], v[156:159], v[168:171], v[0:15]
	v_mfma_f32_32x32x16_bf16 v[32:47], v[156:159], v[172:175], v[32:47]
	v_mfma_f32_32x32x16_bf16 v[16:31], v[152:155], v[168:171], v[16:31]
	v_mfma_f32_32x32x16_bf16 v[48:63], v[152:155], v[172:175], v[48:63]
	v_mfma_f32_32x32x16_bf16 v[64:79], v[140:143], v[148:151], v[64:79]
	v_mfma_f32_32x32x16_bf16 v[96:111], v[140:143], v[144:147], v[96:111]
	v_mfma_f32_32x32x16_bf16 v[80:95], v[132:135], v[148:151], v[80:95]
	v_mfma_f32_32x32x16_bf16 v[112:127], v[132:135], v[144:147], v[112:127]
	v_mfma_f32_32x32x16_bf16 v[0:15], v[136:139], v[148:151], v[0:15]
	v_mfma_f32_32x32x16_bf16 v[32:47], v[136:139], v[144:147], v[32:47]
	v_mfma_f32_32x32x16_bf16 v[16:31], v[128:131], v[148:151], v[16:31]
	v_mfma_f32_32x32x16_bf16 v[48:63], v[128:131], v[144:147], v[48:63]
	s_and_saveexec_b64 s[8:9], s[4:5]
	s_cbranch_execz .LBB0_220
	s_mov_b64 s[10:11], -1
	s_and_b64 vcc, exec, s[6:7]
	s_cbranch_vccz .LBB0_239
	s_cmp_lg_u32 s14, 29
	s_mov_b64 s[6:7], -1
	s_cbranch_scc0 .LBB0_236
	s_waitcnt vmcnt(0)
	s_mov_b64 s[6:7], 0

; #define WAIT_V(n) asm volatile("s_waitcnt vmcnt(" #n ")" ::: "memory")
; #define RAWBAR() do { asm volatile("s_waitcnt lgkmcnt(0)" ::: "memory"); __builtin_amdgcn_s_barrier(); asm volatile("" ::: "memory"); } while (0)
; template <class PF, class EF>
; DI void gemm_stream(int lda, int ldw, int K, unsigned char* smem, PF ptrs, EF epi) {
;     ...
;       if (hh + 3 < nh) { H_DMA(sbase + ((rs + 3) & 3) * SLOT); ap += 64; bp += 64; }
;       if (wm == 1) {
;         if (rem >= 2) WAIT_V(8); else if (rem == 1) WAIT_V(4); else WAIT_V(0);
;       }
;       __builtin_amdgcn_sched_barrier(0);
;       RAWBAR();
;       __builtin_amdgcn_sched_barrier(0);
.LBB0_617:
	s_and_saveexec_b64 s[16:17], s[2:3]
	s_cbranch_execz .LBB0_626
	s_waitcnt lgkmcnt(0)
	s_mov_b64 s[18:19], -1
	s_and_b64 vcc, exec, s[6:7]
	s_cbranch_vccz .LBB0_624
	s_cmp_lg_u32 s35, 13
	s_cbranch_scc0 .LBB0_621
	s_waitcnt vmcnt(0)
	s_mov_b64 s[18:19], 0

; #define WAIT_V(n) asm volatile("s_waitcnt vmcnt(" #n ")" ::: "memory")
; #define RAWBAR() do { asm volatile("s_waitcnt lgkmcnt(0)" ::: "memory"); __builtin_amdgcn_s_barrier(); asm volatile("" ::: "memory"); } while (0)
; #define BAR0() do { asm volatile("" ::: "memory"); __builtin_amdgcn_s_barrier(); asm volatile("" ::: "memory"); } while (0)
; #define H_MMA() do { _Pragma("unroll") for (int ks = 0; ks < 2; ++ks) { _Pragma("unroll") for (int mi = 0; mi < 4; ++mi) {  \
;       acc[mi][0] = MFMA(fa[ks][mi], fb[ks][0], acc[mi][0]);                                                       \
;       acc[mi][1] = MFMA(fa[ks][mi], fb[ks][1], acc[mi][1]); } } } while (0)
; template <class PF, class EF>
; DI void gemm_stream(int lda, int ldw, int K, unsigned char* smem, PF ptrs, EF epi) {
;     ...
;       RAWBAR();
;       __builtin_amdgcn_sched_barrier(0);
;       H_MMA();
;       __builtin_amdgcn_sched_barrier(0);
;       if (wm == 0) {
;         if (rem >= 2) WAIT_V(8); else if (rem == 1) WAIT_V(4); else WAIT_V(0);
;       }
;       BAR0();
.LBB0_626:
	s_or_b64 exec, exec, s[16:17]
	s_barrier
	s_waitcnt lgkmcnt(0)
	v_mfma_f32_32x32x16_bf16 v[96:111], v[164:167], v[168:171], v[96:111]
	v_mfma_f32_32x32x16_bf16 v[112:127], v[164:167], v[172:175], v[112:127]
	v_mfma_f32_32x32x16_bf16 v[64:79], v[160:163], v[168:171], v[64:79]
	v_mfma_f32_32x32x16_bf16 v[80:95], v[160:163], v[172:175], v[80:95]
	v_mfma_f32_32x32x16_bf16 v[32:47], v[156:159], v[168:171], v[32:47]
	v_mfma_f32_32x32x16_bf16 v[48:63], v[156:159], v[172:175], v[48:63]
	v_mfma_f32_32x32x16_bf16 v[0:15], v[152:155], v[168:171], v[0:15]
	v_mfma_f32_32x32x16_bf16 v[16:31], v[152:155], v[172:175], v[16:31]
	v_mfma_f32_32x32x16_bf16 v[96:111], v[140:143], v[148:151], v[96:111]
	v_mfma_f32_32x32x16_bf16 v[112:127], v[140:143], v[144:147], v[112:127]
	v_mfma_f32_32x32x16_bf16 v[64:79], v[132:135], v[148:151], v[64:79]
	v_mfma_f32_32x32x16_bf16 v[80:95], v[132:135], v[144:147], v[80:95]
	v_mfma_f32_32x32x16_bf16 v[32:47], v[136:139], v[148:151], v[32:47]
	v_mfma_f32_32x32x16_bf16 v[48:63], v[136:139], v[144:147], v[48:63]
	v_mfma_f32_32x32x16_bf16 v[0:15], v[128:131], v[148:151], v[0:15]
	v_mfma_f32_32x32x16_bf16 v[16:31], v[128:131], v[144:147], v[16:31]
	s_and_saveexec_b64 s[16:17], s[4:5]
	s_cbranch_execz .LBB0_614
	s_mov_b64 s[18:19], -1
	s_and_b64 vcc, exec, s[6:7]
	s_cbranch_vccz .LBB0_633
	s_cmp_lg_u32 s35, 13
	s_mov_b64 s[6:7], -1
	s_cbranch_scc0 .LBB0_630
	s_waitcnt vmcnt(0)
	s_mov_b64 s[6:7], 0

; #define WAIT_V(n) asm volatile("s_waitcnt vmcnt(" #n ")" ::: "memory")
; #define RAWBAR() do { asm volatile("s_waitcnt lgkmcnt(0)" ::: "memory"); __builtin_amdgcn_s_barrier(); asm volatile("" ::: "memory"); } while (0)
; template <class PF, class EF>
; DI void gemm_stream(int lda, int ldw, int K, unsigned char* smem, PF ptrs, EF epi) {
;     ...
;       if (hh + 3 < nh) { H_DMA(sbase + ((rs + 3) & 3) * SLOT); ap += 64; bp += 64; }
;       if (wm == 1) {
;         if (rem >= 2) WAIT_V(8); else if (rem == 1) WAIT_V(4); else WAIT_V(0);
;       }
;       __builtin_amdgcn_sched_barrier(0);
;       RAWBAR();
;       __builtin_amdgcn_sched_barrier(0);
.LBB0_683:
	s_and_saveexec_b64 s[10:11], s[4:5]
	s_cbranch_execz .LBB0_692
	s_waitcnt lgkmcnt(0)
	s_mov_b64 s[12:13], -1
	s_and_b64 vcc, exec, s[8:9]
	s_cbranch_vccz .LBB0_690
	s_cmp_lg_u32 s39, 29
	s_cbranch_scc0 .LBB0_687
	s_waitcnt vmcnt(0)
	s_mov_b64 s[12:13], 0

; #define WAIT_V(n) asm volatile("s_waitcnt vmcnt(" #n ")" ::: "memory")
; #define RAWBAR() do { asm volatile("s_waitcnt lgkmcnt(0)" ::: "memory"); __builtin_amdgcn_s_barrier(); asm volatile("" ::: "memory"); } while (0)
; #define BAR0() do { asm volatile("" ::: "memory"); __builtin_amdgcn_s_barrier(); asm volatile("" ::: "memory"); } while (0)
; #define H_MMA() do { _Pragma("unroll") for (int ks = 0; ks < 2; ++ks) { _Pragma("unroll") for (int mi = 0; mi < 4; ++mi) {  \
;       acc[mi][0] = MFMA(fa[ks][mi], fb[ks][0], acc[mi][0]);                                                       \
;       acc[mi][1] = MFMA(fa[ks][mi], fb[ks][1], acc[mi][1]); } } } while (0)
; template <class PF, class EF>
; DI void gemm_stream(int lda, int ldw, int K, unsigned char* smem, PF ptrs, EF epi) {
;     ...
;       RAWBAR();
;       __builtin_amdgcn_sched_barrier(0);
;       H_MMA();
;       __builtin_amdgcn_sched_barrier(0);
;       if (wm == 0) {
;         if (rem >= 2) WAIT_V(8); else if (rem == 1) WAIT_V(4); else WAIT_V(0);
;       }
;       BAR0();
.LBB0_692:
	s_or_b64 exec, exec, s[10:11]
	s_barrier
	s_waitcnt lgkmcnt(0)
	v_mfma_f32_32x32x16_bf16 v[96:111], v[164:167], v[168:171], v[96:111]
	v_mfma_f32_32x32x16_bf16 v[112:127], v[164:167], v[172:175], v[112:127]
	v_mfma_f32_32x32x16_bf16 v[64:79], v[160:163], v[168:171], v[64:79]
	v_mfma_f32_32x32x16_bf16 v[80:95], v[160:163], v[172:175], v[80:95]
	v_mfma_f32_32x32x16_bf16 v[32:47], v[156:159], v[168:171], v[32:47]
	v_mfma_f32_32x32x16_bf16 v[48:63], v[156:159], v[172:175], v[48:63]
	v_mfma_f32_32x32x16_bf16 v[0:15], v[152:155], v[168:171], v[0:15]
	v_mfma_f32_32x32x16_bf16 v[16:31], v[152:155], v[172:175], v[16:31]
	v_mfma_f32_32x32x16_bf16 v[96:111], v[140:143], v[148:151], v[96:111]
	v_mfma_f32_32x32x16_bf16 v[112:127], v[140:143], v[144:147], v[112:127]
	v_mfma_f32_32x32x16_bf16 v[64:79], v[132:135], v[148:151], v[64:79]
	v_mfma_f32_32x32x16_bf16 v[80:95], v[132:135], v[144:147], v[80:95]
	v_mfma_f32_32x32x16_bf16 v[32:47], v[136:139], v[148:151], v[32:47]
	v_mfma_f32_32x32x16_bf16 v[48:63], v[136:139], v[144:147], v[48:63]
	v_mfma_f32_32x32x16_bf16 v[0:15], v[128:131], v[148:151], v[0:15]
	v_mfma_f32_32x32x16_bf16 v[16:31], v[128:131], v[144:147], v[16:31]
	s_and_saveexec_b64 s[10:11], s[6:7]
	s_cbranch_execz .LBB0_680
	s_mov_b64 s[12:13], -1
	s_and_b64 vcc, exec, s[8:9]
	s_cbranch_vccz .LBB0_699
	s_cmp_lg_u32 s39, 29
	s_mov_b64 s[8:9], -1
	s_cbranch_scc0 .LBB0_696
	s_waitcnt vmcnt(0)
	s_mov_b64 s[8:9], 0

; #define WAIT_V(n) asm volatile("s_waitcnt vmcnt(" #n ")" ::: "memory")
; #define RAWBAR() do { asm volatile("s_waitcnt lgkmcnt(0)" ::: "memory"); __builtin_amdgcn_s_barrier(); asm volatile("" ::: "memory"); } while (0)
; template <class PF, class EF>
; DI void gemm_stream(int lda, int ldw, int K, unsigned char* smem, PF ptrs, EF epi) {
;     ...
;       if (hh + 3 < nh) { H_DMA(sbase + ((rs + 3) & 3) * SLOT); ap += 64; bp += 64; }
;       if (wm == 1) {
;         if (rem >= 2) WAIT_V(8); else if (rem == 1) WAIT_V(4); else WAIT_V(0);
;       }
;       __builtin_amdgcn_sched_barrier(0);
;       RAWBAR();
;       __builtin_amdgcn_sched_barrier(0);
.LBB0_800:
	s_and_saveexec_b64 s[10:11], s[4:5]
	s_cbranch_execz .LBB0_809
	s_waitcnt lgkmcnt(0)
	s_mov_b64 s[30:31], -1
	s_and_b64 vcc, exec, s[8:9]
	s_cbranch_vccz .LBB0_807
	s_cmp_lg_u32 s44, 29
	s_cbranch_scc0 .LBB0_804
	s_waitcnt vmcnt(0)
	s_mov_b64 s[30:31], 0

; #define WAIT_V(n) asm volatile("s_waitcnt vmcnt(" #n ")" ::: "memory")
; #define RAWBAR() do { asm volatile("s_waitcnt lgkmcnt(0)" ::: "memory"); __builtin_amdgcn_s_barrier(); asm volatile("" ::: "memory"); } while (0)
; #define BAR0() do { asm volatile("" ::: "memory"); __builtin_amdgcn_s_barrier(); asm volatile("" ::: "memory"); } while (0)
; #define H_MMA() do { _Pragma("unroll") for (int ks = 0; ks < 2; ++ks) { _Pragma("unroll") for (int mi = 0; mi < 4; ++mi) {  \
;       acc[mi][0] = MFMA(fa[ks][mi], fb[ks][0], acc[mi][0]);                                                       \
;       acc[mi][1] = MFMA(fa[ks][mi], fb[ks][1], acc[mi][1]); } } } while (0)
; template <class PF, class EF>
; DI void gemm_stream(int lda, int ldw, int K, unsigned char* smem, PF ptrs, EF epi) {
;     ...
;       RAWBAR();
;       __builtin_amdgcn_sched_barrier(0);
;       H_MMA();
;       __builtin_amdgcn_sched_barrier(0);
;       if (wm == 0) {
;         if (rem >= 2) WAIT_V(8); else if (rem == 1) WAIT_V(4); else WAIT_V(0);
;       }
;       BAR0();
.LBB0_809:
	s_or_b64 exec, exec, s[10:11]
	s_barrier
	s_waitcnt lgkmcnt(0)
	v_mfma_f32_32x32x16_bf16 v[96:111], v[164:167], v[168:171], v[96:111]
	v_mfma_f32_32x32x16_bf16 v[112:127], v[164:167], v[172:175], v[112:127]
	v_mfma_f32_32x32x16_bf16 v[64:79], v[160:163], v[168:171], v[64:79]
	v_mfma_f32_32x32x16_bf16 v[80:95], v[160:163], v[172:175], v[80:95]
	v_mfma_f32_32x32x16_bf16 v[32:47], v[156:159], v[168:171], v[32:47]
	v_mfma_f32_32x32x16_bf16 v[48:63], v[156:159], v[172:175], v[48:63]
	v_mfma_f32_32x32x16_bf16 v[0:15], v[152:155], v[168:171], v[0:15]
	v_mfma_f32_32x32x16_bf16 v[16:31], v[152:155], v[172:175], v[16:31]
	v_mfma_f32_32x32x16_bf16 v[96:111], v[140:143], v[148:151], v[96:111]
	v_mfma_f32_32x32x16_bf16 v[112:127], v[140:143], v[144:147], v[112:127]
	v_mfma_f32_32x32x16_bf16 v[64:79], v[132:135], v[148:151], v[64:79]
	v_mfma_f32_32x32x16_bf16 v[80:95], v[132:135], v[144:147], v[80:95]
	v_mfma_f32_32x32x16_bf16 v[32:47], v[136:139], v[148:151], v[32:47]
	v_mfma_f32_32x32x16_bf16 v[48:63], v[136:139], v[144:147], v[48:63]
	v_mfma_f32_32x32x16_bf16 v[0:15], v[128:131], v[148:151], v[0:15]
	v_mfma_f32_32x32x16_bf16 v[16:31], v[128:131], v[144:147], v[16:31]
	s_and_saveexec_b64 s[10:11], s[6:7]
	s_cbranch_execz .LBB0_797
	s_mov_b64 s[30:31], -1
	s_and_b64 vcc, exec, s[8:9]
	s_cbranch_vccz .LBB0_816
	s_cmp_lg_u32 s44, 29
	s_mov_b64 s[8:9], -1
	s_cbranch_scc0 .LBB0_813
	s_waitcnt vmcnt(0)
	s_mov_b64 s[8:9], 0

; #define WAIT_V(n) asm volatile("s_waitcnt vmcnt(" #n ")" ::: "memory")
; #define RAWBAR() do { asm volatile("s_waitcnt lgkmcnt(0)" ::: "memory"); __builtin_amdgcn_s_barrier(); asm volatile("" ::: "memory"); } while (0)
; template <class PF, class EF>
; DI void gemm_stream(int lda, int ldw, int K, unsigned char* smem, PF ptrs, EF epi) {
;     ...
;       if (hh + 3 < nh) { H_DMA(sbase + ((rs + 3) & 3) * SLOT); ap += 64; bp += 64; }
;       if (wm == 1) {
;         if (rem >= 2) WAIT_V(8); else if (rem == 1) WAIT_V(4); else WAIT_V(0);
;       }
;       __builtin_amdgcn_sched_barrier(0);
;       RAWBAR();
;       __builtin_amdgcn_sched_barrier(0);
.LBB0_846:
	s_and_saveexec_b64 s[28:29], s[4:5]
	s_cbranch_execz .LBB0_855
	s_waitcnt lgkmcnt(0)
	s_mov_b64 s[30:31], -1
	s_and_b64 vcc, exec, s[8:9]
	s_cbranch_vccz .LBB0_853
	s_cmpk_lg_i32 s45, 0x55
	s_cbranch_scc0 .LBB0_850
	s_waitcnt vmcnt(0)
	s_mov_b64 s[30:31], 0

; #define WAIT_V(n) asm volatile("s_waitcnt vmcnt(" #n ")" ::: "memory")
; #define RAWBAR() do { asm volatile("s_waitcnt lgkmcnt(0)" ::: "memory"); __builtin_amdgcn_s_barrier(); asm volatile("" ::: "memory"); } while (0)
; #define BAR0() do { asm volatile("" ::: "memory"); __builtin_amdgcn_s_barrier(); asm volatile("" ::: "memory"); } while (0)
; #define H_MMA() do { _Pragma("unroll") for (int ks = 0; ks < 2; ++ks) { _Pragma("unroll") for (int mi = 0; mi < 4; ++mi) {  \
;       acc[mi][0] = MFMA(fa[ks][mi], fb[ks][0], acc[mi][0]);                                                       \
;       acc[mi][1] = MFMA(fa[ks][mi], fb[ks][1], acc[mi][1]); } } } while (0)
; template <class PF, class EF>
; DI void gemm_stream(int lda, int ldw, int K, unsigned char* smem, PF ptrs, EF epi) {
;     ...
;       RAWBAR();
;       __builtin_amdgcn_sched_barrier(0);
;       H_MMA();
;       __builtin_amdgcn_sched_barrier(0);
;       if (wm == 0) {
;         if (rem >= 2) WAIT_V(8); else if (rem == 1) WAIT_V(4); else WAIT_V(0);
;       }
;       BAR0();
.LBB0_855:
	s_or_b64 exec, exec, s[28:29]
	s_barrier
	s_waitcnt lgkmcnt(0)
	v_mfma_f32_32x32x16_bf16 v[96:111], v[164:167], v[168:171], v[96:111]
	v_mfma_f32_32x32x16_bf16 v[112:127], v[164:167], v[172:175], v[112:127]
	v_mfma_f32_32x32x16_bf16 v[64:79], v[160:163], v[168:171], v[64:79]
	v_mfma_f32_32x32x16_bf16 v[80:95], v[160:163], v[172:175], v[80:95]
	v_mfma_f32_32x32x16_bf16 v[32:47], v[156:159], v[168:171], v[32:47]
	v_mfma_f32_32x32x16_bf16 v[48:63], v[156:159], v[172:175], v[48:63]
	v_mfma_f32_32x32x16_bf16 v[0:15], v[152:155], v[168:171], v[0:15]
	v_mfma_f32_32x32x16_bf16 v[16:31], v[152:155], v[172:175], v[16:31]
	v_mfma_f32_32x32x16_bf16 v[96:111], v[140:143], v[148:151], v[96:111]
	v_mfma_f32_32x32x16_bf16 v[112:127], v[140:143], v[144:147], v[112:127]
	v_mfma_f32_32x32x16_bf16 v[64:79], v[132:135], v[148:151], v[64:79]
	v_mfma_f32_32x32x16_bf16 v[80:95], v[132:135], v[144:147], v[80:95]
	v_mfma_f32_32x32x16_bf16 v[32:47], v[136:139], v[148:151], v[32:47]
	v_mfma_f32_32x32x16_bf16 v[48:63], v[136:139], v[144:147], v[48:63]
	v_mfma_f32_32x32x16_bf16 v[0:15], v[128:131], v[148:151], v[0:15]
	v_mfma_f32_32x32x16_bf16 v[16:31], v[128:131], v[144:147], v[16:31]
	s_and_saveexec_b64 s[28:29], s[6:7]
	s_cbranch_execz .LBB0_843
	s_mov_b64 s[30:31], -1
	s_and_b64 vcc, exec, s[8:9]
	s_cbranch_vccz .LBB0_862
	s_cmpk_lg_i32 s45, 0x55
	s_mov_b64 s[8:9], -1
	s_cbranch_scc0 .LBB0_859
	s_waitcnt vmcnt(0)
	s_mov_b64 s[8:9], 0
